# P6 gate/up epilogue fast path for full latent tiles: no per-row validity branches, one 32-bit offset add per row with SGPR-base stores; per-element exp2 / IEEE-division / bf16-RNE sequence unchanged
# speedup vs baseline: 1.0128x; 1.0128x over previous
; __device__ __forceinline__ float siluf(float x) { return x / (1.f + __expf(-x)); }
; __device__ __forceinline__ void moe_up_tile(const Params& p, char* smem, int l, int e, int nt, int b, int mt, bool isctx) {
;     ...
;   auto epi = [&](f32x4 (&acc)[8][4], int wr, int wc, int fr, int fq) {
; #pragma unroll
;     for (int m = 0; m < 8; ++m)
; #pragma unroll
;       for (int j = 0; j < 4; ++j) {
;         int slot = wr * 128 + m * 16 + fq * 4 + j;
;         if (slot < nvalid) {
;           u16* dst = isctx ? ACTC + ((size_t)(((slot >> 5) * 16 + e) * 32 + (slot & 31))) * 2048 : ACTL + (size_t)slot * 2048;
; #pragma unroll
;           for (int n = 0; n < 2; ++n) {
;             int f = nt * 64 + wc * 32 + n * 16 + fr;
;             float g = acc[m][n][j], uu = acc[m][n + 2][j];
;             dst[f] = f2bf(siluf(g) * uu);
;           }
;         }
;       }
.LBB0_1673:
	s_or_b64 exec, exec, s[0:1]
	s_lshl_b32 s0, s15, 4
	s_add_i32 s0, s13, s0
	s_ashr_i32 s1, s0, 31
	s_lshl_b64 s[0:1], s[0:1], 22
	s_add_u32 s0, s4, s0
	s_addc_u32 s1, s5, s1
	s_lshl_b32 s6, s11, 12
	s_add_u32 s0, s0, s6
	s_addc_u32 s1, s1, 0
	s_add_u32 s6, s0, 0x2e4e0100
	v_lshlrev_b32_e32 v0, 2, v193
	s_addc_u32 s7, s1, 0
	v_and_b32_e32 v2, 12, v0
	s_add_u32 s4, s4, 0x364e0100
	s_waitcnt lgkmcnt(3)
	v_or_b32_e32 v132, v2, v179
	v_ashrrev_i32_e32 v3, 1, v192
	s_addc_u32 s5, s5, 0
	v_lshl_or_b32 v0, v211, 5, v212
	v_and_b32_e32 v3, 0xffffffc0, v3
	v_cmp_gt_i32_e32 vcc, s14, v132
	s_waitcnt lgkmcnt(0)
	s_barrier
	s_cmpk_lt_i32 s12, 0x1000
	s_cbranch_scc0 .Lp6_epi_slow
	v_lshlrev_b32_e32 v248, 12, v132
	v_lshlrev_b32_e32 v249, 1, v0
	v_lshl_or_b32 v249, s10, 7, v249
	v_add_u32_e32 v248, v248, v249
	v_add_u32_e32 v250, 0x0, v248
	v_mul_f32_e32 v240, 0xbfb8aa3b, v128
	v_exp_f32_e32 v240, v240
	s_nop 0
	v_add_f32_e32 v240, 1.0, v240
	v_div_scale_f32 v241, s[8:9], v240, v240, v128
	v_rcp_f32_e32 v242, v241
	s_nop 0
	v_fma_f32 v243, -v241, v242, 1.0
	v_fmac_f32_e32 v242, v243, v242
	v_div_scale_f32 v243, vcc, v128, v240, v128
	v_mul_f32_e32 v245, v243, v242
	v_fma_f32 v246, -v241, v245, v243
	v_fmac_f32_e32 v245, v246, v242
	v_fma_f32 v241, -v241, v245, v243
	v_div_fmas_f32 v241, v241, v242, v245
	v_div_fixup_f32 v128, v241, v240, v128
	v_mul_f32_e32 v124, v124, v128
	v_bfe_u32 v128, v124, 16, 1
	v_add3_u32 v124, v124, v128, s33
	global_store_short_d16_hi v250, v124, s[6:7]
	v_mul_f32_e32 v240, 0xbfb8aa3b, v120
	v_exp_f32_e32 v240, v240
	s_nop 0
	v_add_f32_e32 v240, 1.0, v240
	v_div_scale_f32 v241, s[8:9], v240, v240, v120
	v_rcp_f32_e32 v242, v241
	s_nop 0
	v_fma_f32 v243, -v241, v242, 1.0
	v_fmac_f32_e32 v242, v243, v242
	v_div_scale_f32 v243, vcc, v120, v240, v120
	v_mul_f32_e32 v245, v243, v242
	v_fma_f32 v246, -v241, v245, v243
	v_fmac_f32_e32 v245, v246, v242
	v_fma_f32 v241, -v241, v245, v243
	v_div_fmas_f32 v241, v241, v242, v245
	v_div_fixup_f32 v120, v241, v240, v120
	v_mul_f32_e32 v116, v116, v120
	v_bfe_u32 v120, v116, 16, 1
	v_add3_u32 v116, v116, v120, s33
	global_store_short_d16_hi v250, v116, s[6:7] offset:32
	v_add_u32_e32 v250, 0x1000, v248
	v_mul_f32_e32 v240, 0xbfb8aa3b, v129
	v_exp_f32_e32 v240, v240
	s_nop 0
	v_add_f32_e32 v240, 1.0, v240
	v_div_scale_f32 v241, s[8:9], v240, v240, v129
	v_rcp_f32_e32 v242, v241
	s_nop 0
	v_fma_f32 v243, -v241, v242, 1.0
	v_fmac_f32_e32 v242, v243, v242
	v_div_scale_f32 v243, vcc, v129, v240, v129
	v_mul_f32_e32 v245, v243, v242
	v_fma_f32 v246, -v241, v245, v243
	v_fmac_f32_e32 v245, v246, v242
	v_fma_f32 v241, -v241, v245, v243
	v_div_fmas_f32 v241, v241, v242, v245
	v_div_fixup_f32 v129, v241, v240, v129
	v_mul_f32_e32 v125, v125, v129
	v_bfe_u32 v129, v125, 16, 1
	v_add3_u32 v125, v125, v129, s33
	global_store_short_d16_hi v250, v125, s[6:7]
	v_mul_f32_e32 v240, 0xbfb8aa3b, v121
	v_exp_f32_e32 v240, v240
	s_nop 0
	v_add_f32_e32 v240, 1.0, v240
	v_div_scale_f32 v241, s[8:9], v240, v240, v121
	v_rcp_f32_e32 v242, v241
	s_nop 0
	v_fma_f32 v243, -v241, v242, 1.0
	v_fmac_f32_e32 v242, v243, v242
	v_div_scale_f32 v243, vcc, v121, v240, v121
	v_mul_f32_e32 v245, v243, v242
	v_fma_f32 v246, -v241, v245, v243
	v_fmac_f32_e32 v245, v246, v242
	v_fma_f32 v241, -v241, v245, v243
	v_div_fmas_f32 v241, v241, v242, v245
	v_div_fixup_f32 v121, v241, v240, v121
	v_mul_f32_e32 v117, v117, v121
	v_bfe_u32 v121, v117, 16, 1
	v_add3_u32 v117, v117, v121, s33
	global_store_short_d16_hi v250, v117, s[6:7] offset:32
	v_add_u32_e32 v250, 0x2000, v248
	v_mul_f32_e32 v240, 0xbfb8aa3b, v130
	v_exp_f32_e32 v240, v240
	s_nop 0
	v_add_f32_e32 v240, 1.0, v240
	v_div_scale_f32 v241, s[8:9], v240, v240, v130
	v_rcp_f32_e32 v242, v241
	s_nop 0
	v_fma_f32 v243, -v241, v242, 1.0
	v_fmac_f32_e32 v242, v243, v242
	v_div_scale_f32 v243, vcc, v130, v240, v130
	v_mul_f32_e32 v245, v243, v242
	v_fma_f32 v246, -v241, v245, v243
	v_fmac_f32_e32 v245, v246, v242
	v_fma_f32 v241, -v241, v245, v243
	v_div_fmas_f32 v241, v241, v242, v245
	v_div_fixup_f32 v130, v241, v240, v130
	v_mul_f32_e32 v126, v126, v130
	v_bfe_u32 v130, v126, 16, 1
	v_add3_u32 v126, v126, v130, s33
	global_store_short_d16_hi v250, v126, s[6:7]
	v_mul_f32_e32 v240, 0xbfb8aa3b, v122
	v_exp_f32_e32 v240, v240
	s_nop 0
	v_add_f32_e32 v240, 1.0, v240
	v_div_scale_f32 v241, s[8:9], v240, v240, v122
	v_rcp_f32_e32 v242, v241
	s_nop 0
	v_fma_f32 v243, -v241, v242, 1.0
	v_fmac_f32_e32 v242, v243, v242
	v_div_scale_f32 v243, vcc, v122, v240, v122
	v_mul_f32_e32 v245, v243, v242
	v_fma_f32 v246, -v241, v245, v243
	v_fmac_f32_e32 v245, v246, v242
	v_fma_f32 v241, -v241, v245, v243
	v_div_fmas_f32 v241, v241, v242, v245
	v_div_fixup_f32 v122, v241, v240, v122
	v_mul_f32_e32 v118, v118, v122
	v_bfe_u32 v122, v118, 16, 1
	v_add3_u32 v118, v118, v122, s33
	global_store_short_d16_hi v250, v118, s[6:7] offset:32
	v_add_u32_e32 v250, 0x3000, v248
	v_mul_f32_e32 v240, 0xbfb8aa3b, v131
	v_exp_f32_e32 v240, v240
	s_nop 0
	v_add_f32_e32 v240, 1.0, v240
	v_div_scale_f32 v241, s[8:9], v240, v240, v131
	v_rcp_f32_e32 v242, v241
	s_nop 0
	v_fma_f32 v243, -v241, v242, 1.0
	v_fmac_f32_e32 v242, v243, v242
	v_div_scale_f32 v243, vcc, v131, v240, v131
	v_mul_f32_e32 v245, v243, v242
	v_fma_f32 v246, -v241, v245, v243
	v_fmac_f32_e32 v245, v246, v242
	v_fma_f32 v241, -v241, v245, v243
	v_div_fmas_f32 v241, v241, v242, v245
	v_div_fixup_f32 v131, v241, v240, v131
	v_mul_f32_e32 v127, v127, v131
	v_bfe_u32 v131, v127, 16, 1
	v_add3_u32 v127, v127, v131, s33
	global_store_short_d16_hi v250, v127, s[6:7]
	v_mul_f32_e32 v240, 0xbfb8aa3b, v123
	v_exp_f32_e32 v240, v240
	s_nop 0
; __device__ __forceinline__ float siluf(float x) { return x / (1.f + __expf(-x)); }
; __device__ __forceinline__ void moe_up_tile(const Params& p, char* smem, int l, int e, int nt, int b, int mt, bool isctx) {
;     ...
;   auto epi = [&](f32x4 (&acc)[8][4], int wr, int wc, int fr, int fq) {
; #pragma unroll
;     for (int m = 0; m < 8; ++m)
; #pragma unroll
;       for (int j = 0; j < 4; ++j) {
;         int slot = wr * 128 + m * 16 + fq * 4 + j;
;         if (slot < nvalid) {
;           u16* dst = isctx ? ACTC + ((size_t)(((slot >> 5) * 16 + e) * 32 + (slot & 31))) * 2048 : ACTL + (size_t)slot * 2048;
; #pragma unroll
;           for (int n = 0; n < 2; ++n) {
;             int f = nt * 64 + wc * 32 + n * 16 + fr;
;             float g = acc[m][n][j], uu = acc[m][n + 2][j];
;             dst[f] = f2bf(siluf(g) * uu);
;           }
;         }
;       }
	v_add_f32_e32 v240, 1.0, v240
	v_div_scale_f32 v241, s[8:9], v240, v240, v123
	v_rcp_f32_e32 v242, v241
	s_nop 0
	v_fma_f32 v243, -v241, v242, 1.0
	v_fmac_f32_e32 v242, v243, v242
	v_div_scale_f32 v243, vcc, v123, v240, v123
	v_mul_f32_e32 v245, v243, v242
	v_fma_f32 v246, -v241, v245, v243
	v_fmac_f32_e32 v245, v246, v242
	v_fma_f32 v241, -v241, v245, v243
	v_div_fmas_f32 v241, v241, v242, v245
	v_div_fixup_f32 v123, v241, v240, v123
	v_mul_f32_e32 v119, v119, v123
	v_bfe_u32 v123, v119, 16, 1
	v_add3_u32 v119, v119, v123, s33
	global_store_short_d16_hi v250, v119, s[6:7] offset:32
	v_add_u32_e32 v250, 0x10000, v248
	v_mul_f32_e32 v240, 0xbfb8aa3b, v112
	v_exp_f32_e32 v240, v240
	s_nop 0
	v_add_f32_e32 v240, 1.0, v240
	v_div_scale_f32 v241, s[8:9], v240, v240, v112
	v_rcp_f32_e32 v242, v241
	s_nop 0
	v_fma_f32 v243, -v241, v242, 1.0
	v_fmac_f32_e32 v242, v243, v242
	v_div_scale_f32 v243, vcc, v112, v240, v112
	v_mul_f32_e32 v245, v243, v242
	v_fma_f32 v246, -v241, v245, v243
	v_fmac_f32_e32 v245, v246, v242
	v_fma_f32 v241, -v241, v245, v243
	v_div_fmas_f32 v241, v241, v242, v245
	v_div_fixup_f32 v112, v241, v240, v112
	v_mul_f32_e32 v108, v108, v112
	v_bfe_u32 v112, v108, 16, 1
	v_add3_u32 v108, v108, v112, s33
	global_store_short_d16_hi v250, v108, s[6:7]
	v_mul_f32_e32 v240, 0xbfb8aa3b, v104
	v_exp_f32_e32 v240, v240
	s_nop 0
	v_add_f32_e32 v240, 1.0, v240
	v_div_scale_f32 v241, s[8:9], v240, v240, v104
	v_rcp_f32_e32 v242, v241
	s_nop 0
	v_fma_f32 v243, -v241, v242, 1.0
	v_fmac_f32_e32 v242, v243, v242
	v_div_scale_f32 v243, vcc, v104, v240, v104
	v_mul_f32_e32 v245, v243, v242
	v_fma_f32 v246, -v241, v245, v243
	v_fmac_f32_e32 v245, v246, v242
	v_fma_f32 v241, -v241, v245, v243
	v_div_fmas_f32 v241, v241, v242, v245
	v_div_fixup_f32 v104, v241, v240, v104
	v_mul_f32_e32 v100, v100, v104
	v_bfe_u32 v104, v100, 16, 1
	v_add3_u32 v100, v100, v104, s33
	global_store_short_d16_hi v250, v100, s[6:7] offset:32
	v_add_u32_e32 v250, 0x11000, v248
	v_mul_f32_e32 v240, 0xbfb8aa3b, v113
	v_exp_f32_e32 v240, v240
	s_nop 0
	v_add_f32_e32 v240, 1.0, v240
	v_div_scale_f32 v241, s[8:9], v240, v240, v113
	v_rcp_f32_e32 v242, v241
	s_nop 0
	v_fma_f32 v243, -v241, v242, 1.0
	v_fmac_f32_e32 v242, v243, v242
	v_div_scale_f32 v243, vcc, v113, v240, v113
	v_mul_f32_e32 v245, v243, v242
	v_fma_f32 v246, -v241, v245, v243
	v_fmac_f32_e32 v245, v246, v242
	v_fma_f32 v241, -v241, v245, v243
	v_div_fmas_f32 v241, v241, v242, v245
	v_div_fixup_f32 v113, v241, v240, v113
	v_mul_f32_e32 v109, v109, v113
	v_bfe_u32 v113, v109, 16, 1
	v_add3_u32 v109, v109, v113, s33
	global_store_short_d16_hi v250, v109, s[6:7]
	v_mul_f32_e32 v240, 0xbfb8aa3b, v105
	v_exp_f32_e32 v240, v240
	s_nop 0
	v_add_f32_e32 v240, 1.0, v240
	v_div_scale_f32 v241, s[8:9], v240, v240, v105
	v_rcp_f32_e32 v242, v241
	s_nop 0
	v_fma_f32 v243, -v241, v242, 1.0
	v_fmac_f32_e32 v242, v243, v242
	v_div_scale_f32 v243, vcc, v105, v240, v105
	v_mul_f32_e32 v245, v243, v242
	v_fma_f32 v246, -v241, v245, v243
	v_fmac_f32_e32 v245, v246, v242
	v_fma_f32 v241, -v241, v245, v243
	v_div_fmas_f32 v241, v241, v242, v245
	v_div_fixup_f32 v105, v241, v240, v105
	v_mul_f32_e32 v101, v101, v105
	v_bfe_u32 v105, v101, 16, 1
	v_add3_u32 v101, v101, v105, s33
	global_store_short_d16_hi v250, v101, s[6:7] offset:32
	v_add_u32_e32 v250, 0x12000, v248
	v_mul_f32_e32 v240, 0xbfb8aa3b, v114
	v_exp_f32_e32 v240, v240
	s_nop 0
	v_add_f32_e32 v240, 1.0, v240
	v_div_scale_f32 v241, s[8:9], v240, v240, v114
	v_rcp_f32_e32 v242, v241
	s_nop 0
	v_fma_f32 v243, -v241, v242, 1.0
	v_fmac_f32_e32 v242, v243, v242
	v_div_scale_f32 v243, vcc, v114, v240, v114
	v_mul_f32_e32 v245, v243, v242
	v_fma_f32 v246, -v241, v245, v243
	v_fmac_f32_e32 v245, v246, v242
	v_fma_f32 v241, -v241, v245, v243
	v_div_fmas_f32 v241, v241, v242, v245
	v_div_fixup_f32 v114, v241, v240, v114
	v_mul_f32_e32 v110, v110, v114
	v_bfe_u32 v114, v110, 16, 1
	v_add3_u32 v110, v110, v114, s33
	global_store_short_d16_hi v250, v110, s[6:7]
	v_mul_f32_e32 v240, 0xbfb8aa3b, v106
	v_exp_f32_e32 v240, v240
	s_nop 0
	v_add_f32_e32 v240, 1.0, v240
	v_div_scale_f32 v241, s[8:9], v240, v240, v106
	v_rcp_f32_e32 v242, v241
	s_nop 0
	v_fma_f32 v243, -v241, v242, 1.0
	v_fmac_f32_e32 v242, v243, v242
	v_div_scale_f32 v243, vcc, v106, v240, v106
	v_mul_f32_e32 v245, v243, v242
	v_fma_f32 v246, -v241, v245, v243
	v_fmac_f32_e32 v245, v246, v242
	v_fma_f32 v241, -v241, v245, v243
	v_div_fmas_f32 v241, v241, v242, v245
	v_div_fixup_f32 v106, v241, v240, v106
	v_mul_f32_e32 v102, v102, v106
	v_bfe_u32 v106, v102, 16, 1
	v_add3_u32 v102, v102, v106, s33
	global_store_short_d16_hi v250, v102, s[6:7] offset:32
	v_add_u32_e32 v250, 0x13000, v248
	v_mul_f32_e32 v240, 0xbfb8aa3b, v115
	v_exp_f32_e32 v240, v240
	s_nop 0
	v_add_f32_e32 v240, 1.0, v240
	v_div_scale_f32 v241, s[8:9], v240, v240, v115
	v_rcp_f32_e32 v242, v241
	s_nop 0
	v_fma_f32 v243, -v241, v242, 1.0
	v_fmac_f32_e32 v242, v243, v242
	v_div_scale_f32 v243, vcc, v115, v240, v115
	v_mul_f32_e32 v245, v243, v242
	v_fma_f32 v246, -v241, v245, v243
	v_fmac_f32_e32 v245, v246, v242
	v_fma_f32 v241, -v241, v245, v243
	v_div_fmas_f32 v241, v241, v242, v245
	v_div_fixup_f32 v115, v241, v240, v115
	v_mul_f32_e32 v111, v111, v115
	v_bfe_u32 v115, v111, 16, 1
	v_add3_u32 v111, v111, v115, s33
	global_store_short_d16_hi v250, v111, s[6:7]
	v_mul_f32_e32 v240, 0xbfb8aa3b, v107
	v_exp_f32_e32 v240, v240
	s_nop 0
	v_add_f32_e32 v240, 1.0, v240
	v_div_scale_f32 v241, s[8:9], v240, v240, v107
	v_rcp_f32_e32 v242, v241
	s_nop 0
	v_fma_f32 v243, -v241, v242, 1.0
	v_fmac_f32_e32 v242, v243, v242
	v_div_scale_f32 v243, vcc, v107, v240, v107
; __device__ __forceinline__ float siluf(float x) { return x / (1.f + __expf(-x)); }
; __device__ __forceinline__ void moe_up_tile(const Params& p, char* smem, int l, int e, int nt, int b, int mt, bool isctx) {
;     ...
;   auto epi = [&](f32x4 (&acc)[8][4], int wr, int wc, int fr, int fq) {
; #pragma unroll
;     for (int m = 0; m < 8; ++m)
; #pragma unroll
;       for (int j = 0; j < 4; ++j) {
;         int slot = wr * 128 + m * 16 + fq * 4 + j;
;         if (slot < nvalid) {
;           u16* dst = isctx ? ACTC + ((size_t)(((slot >> 5) * 16 + e) * 32 + (slot & 31))) * 2048 : ACTL + (size_t)slot * 2048;
; #pragma unroll
;           for (int n = 0; n < 2; ++n) {
;             int f = nt * 64 + wc * 32 + n * 16 + fr;
;             float g = acc[m][n][j], uu = acc[m][n + 2][j];
;             dst[f] = f2bf(siluf(g) * uu);
;           }
;         }
;       }
	v_mul_f32_e32 v245, v243, v242
	v_fma_f32 v246, -v241, v245, v243
	v_fmac_f32_e32 v245, v246, v242
	v_fma_f32 v241, -v241, v245, v243
	v_div_fmas_f32 v241, v241, v242, v245
	v_div_fixup_f32 v107, v241, v240, v107
	v_mul_f32_e32 v103, v103, v107
	v_bfe_u32 v107, v103, 16, 1
	v_add3_u32 v103, v103, v107, s33
	global_store_short_d16_hi v250, v103, s[6:7] offset:32
	v_add_u32_e32 v250, 0x20000, v248
	v_mul_f32_e32 v240, 0xbfb8aa3b, v96
	v_exp_f32_e32 v240, v240
	s_nop 0
	v_add_f32_e32 v240, 1.0, v240
	v_div_scale_f32 v241, s[8:9], v240, v240, v96
	v_rcp_f32_e32 v242, v241
	s_nop 0
	v_fma_f32 v243, -v241, v242, 1.0
	v_fmac_f32_e32 v242, v243, v242
	v_div_scale_f32 v243, vcc, v96, v240, v96
	v_mul_f32_e32 v245, v243, v242
	v_fma_f32 v246, -v241, v245, v243
	v_fmac_f32_e32 v245, v246, v242
	v_fma_f32 v241, -v241, v245, v243
	v_div_fmas_f32 v241, v241, v242, v245
	v_div_fixup_f32 v96, v241, v240, v96
	v_mul_f32_e32 v92, v92, v96
	v_bfe_u32 v96, v92, 16, 1
	v_add3_u32 v92, v92, v96, s33
	global_store_short_d16_hi v250, v92, s[6:7]
	v_mul_f32_e32 v240, 0xbfb8aa3b, v88
	v_exp_f32_e32 v240, v240
	s_nop 0
	v_add_f32_e32 v240, 1.0, v240
	v_div_scale_f32 v241, s[8:9], v240, v240, v88
	v_rcp_f32_e32 v242, v241
	s_nop 0
	v_fma_f32 v243, -v241, v242, 1.0
	v_fmac_f32_e32 v242, v243, v242
	v_div_scale_f32 v243, vcc, v88, v240, v88
	v_mul_f32_e32 v245, v243, v242
	v_fma_f32 v246, -v241, v245, v243
	v_fmac_f32_e32 v245, v246, v242
	v_fma_f32 v241, -v241, v245, v243
	v_div_fmas_f32 v241, v241, v242, v245
	v_div_fixup_f32 v88, v241, v240, v88
	v_mul_f32_e32 v84, v84, v88
	v_bfe_u32 v88, v84, 16, 1
	v_add3_u32 v84, v84, v88, s33
	global_store_short_d16_hi v250, v84, s[6:7] offset:32
	v_add_u32_e32 v250, 0x21000, v248
	v_mul_f32_e32 v240, 0xbfb8aa3b, v97
	v_exp_f32_e32 v240, v240
	s_nop 0
	v_add_f32_e32 v240, 1.0, v240
	v_div_scale_f32 v241, s[8:9], v240, v240, v97
	v_rcp_f32_e32 v242, v241
	s_nop 0
	v_fma_f32 v243, -v241, v242, 1.0
	v_fmac_f32_e32 v242, v243, v242
	v_div_scale_f32 v243, vcc, v97, v240, v97
	v_mul_f32_e32 v245, v243, v242
	v_fma_f32 v246, -v241, v245, v243
	v_fmac_f32_e32 v245, v246, v242
	v_fma_f32 v241, -v241, v245, v243
	v_div_fmas_f32 v241, v241, v242, v245
	v_div_fixup_f32 v97, v241, v240, v97
	v_mul_f32_e32 v93, v93, v97
	v_bfe_u32 v97, v93, 16, 1
	v_add3_u32 v93, v93, v97, s33
	global_store_short_d16_hi v250, v93, s[6:7]
	v_mul_f32_e32 v240, 0xbfb8aa3b, v89
	v_exp_f32_e32 v240, v240
	s_nop 0
	v_add_f32_e32 v240, 1.0, v240
	v_div_scale_f32 v241, s[8:9], v240, v240, v89
	v_rcp_f32_e32 v242, v241
	s_nop 0
	v_fma_f32 v243, -v241, v242, 1.0
	v_fmac_f32_e32 v242, v243, v242
	v_div_scale_f32 v243, vcc, v89, v240, v89
	v_mul_f32_e32 v245, v243, v242
	v_fma_f32 v246, -v241, v245, v243
	v_fmac_f32_e32 v245, v246, v242
	v_fma_f32 v241, -v241, v245, v243
	v_div_fmas_f32 v241, v241, v242, v245
	v_div_fixup_f32 v89, v241, v240, v89
	v_mul_f32_e32 v85, v85, v89
	v_bfe_u32 v89, v85, 16, 1
	v_add3_u32 v85, v85, v89, s33
	global_store_short_d16_hi v250, v85, s[6:7] offset:32
	v_add_u32_e32 v250, 0x22000, v248
	v_mul_f32_e32 v240, 0xbfb8aa3b, v98
	v_exp_f32_e32 v240, v240
	s_nop 0
	v_add_f32_e32 v240, 1.0, v240
	v_div_scale_f32 v241, s[8:9], v240, v240, v98
	v_rcp_f32_e32 v242, v241
	s_nop 0
	v_fma_f32 v243, -v241, v242, 1.0
	v_fmac_f32_e32 v242, v243, v242
	v_div_scale_f32 v243, vcc, v98, v240, v98
	v_mul_f32_e32 v245, v243, v242
	v_fma_f32 v246, -v241, v245, v243
	v_fmac_f32_e32 v245, v246, v242
	v_fma_f32 v241, -v241, v245, v243
	v_div_fmas_f32 v241, v241, v242, v245
	v_div_fixup_f32 v98, v241, v240, v98
	v_mul_f32_e32 v94, v94, v98
	v_bfe_u32 v98, v94, 16, 1
	v_add3_u32 v94, v94, v98, s33
	global_store_short_d16_hi v250, v94, s[6:7]
	v_mul_f32_e32 v240, 0xbfb8aa3b, v90
	v_exp_f32_e32 v240, v240
	s_nop 0
	v_add_f32_e32 v240, 1.0, v240
	v_div_scale_f32 v241, s[8:9], v240, v240, v90
	v_rcp_f32_e32 v242, v241
	s_nop 0
	v_fma_f32 v243, -v241, v242, 1.0
	v_fmac_f32_e32 v242, v243, v242
	v_div_scale_f32 v243, vcc, v90, v240, v90
	v_mul_f32_e32 v245, v243, v242
	v_fma_f32 v246, -v241, v245, v243
	v_fmac_f32_e32 v245, v246, v242
	v_fma_f32 v241, -v241, v245, v243
	v_div_fmas_f32 v241, v241, v242, v245
	v_div_fixup_f32 v90, v241, v240, v90
	v_mul_f32_e32 v86, v86, v90
	v_bfe_u32 v90, v86, 16, 1
	v_add3_u32 v86, v86, v90, s33
	global_store_short_d16_hi v250, v86, s[6:7] offset:32
	v_add_u32_e32 v250, 0x23000, v248
	v_mul_f32_e32 v240, 0xbfb8aa3b, v99
	v_exp_f32_e32 v240, v240
	s_nop 0
	v_add_f32_e32 v240, 1.0, v240
	v_div_scale_f32 v241, s[8:9], v240, v240, v99
	v_rcp_f32_e32 v242, v241
	s_nop 0
	v_fma_f32 v243, -v241, v242, 1.0
	v_fmac_f32_e32 v242, v243, v242
	v_div_scale_f32 v243, vcc, v99, v240, v99
	v_mul_f32_e32 v245, v243, v242
	v_fma_f32 v246, -v241, v245, v243
	v_fmac_f32_e32 v245, v246, v242
	v_fma_f32 v241, -v241, v245, v243
	v_div_fmas_f32 v241, v241, v242, v245
	v_div_fixup_f32 v99, v241, v240, v99
	v_mul_f32_e32 v95, v95, v99
	v_bfe_u32 v99, v95, 16, 1
	v_add3_u32 v95, v95, v99, s33
	global_store_short_d16_hi v250, v95, s[6:7]
	v_mul_f32_e32 v240, 0xbfb8aa3b, v91
	v_exp_f32_e32 v240, v240
	s_nop 0
	v_add_f32_e32 v240, 1.0, v240
	v_div_scale_f32 v241, s[8:9], v240, v240, v91
	v_rcp_f32_e32 v242, v241
	s_nop 0
	v_fma_f32 v243, -v241, v242, 1.0
	v_fmac_f32_e32 v242, v243, v242
	v_div_scale_f32 v243, vcc, v91, v240, v91
	v_mul_f32_e32 v245, v243, v242
	v_fma_f32 v246, -v241, v245, v243
	v_fmac_f32_e32 v245, v246, v242
	v_fma_f32 v241, -v241, v245, v243
	v_div_fmas_f32 v241, v241, v242, v245
	v_div_fixup_f32 v91, v241, v240, v91
	v_mul_f32_e32 v87, v87, v91
	v_bfe_u32 v91, v87, 16, 1
	v_add3_u32 v87, v87, v91, s33
	global_store_short_d16_hi v250, v87, s[6:7] offset:32
; __device__ __forceinline__ float siluf(float x) { return x / (1.f + __expf(-x)); }
; __device__ __forceinline__ void moe_up_tile(const Params& p, char* smem, int l, int e, int nt, int b, int mt, bool isctx) {
;     ...
;   auto epi = [&](f32x4 (&acc)[8][4], int wr, int wc, int fr, int fq) {
; #pragma unroll
;     for (int m = 0; m < 8; ++m)
; #pragma unroll
;       for (int j = 0; j < 4; ++j) {
;         int slot = wr * 128 + m * 16 + fq * 4 + j;
;         if (slot < nvalid) {
;           u16* dst = isctx ? ACTC + ((size_t)(((slot >> 5) * 16 + e) * 32 + (slot & 31))) * 2048 : ACTL + (size_t)slot * 2048;
; #pragma unroll
;           for (int n = 0; n < 2; ++n) {
;             int f = nt * 64 + wc * 32 + n * 16 + fr;
;             float g = acc[m][n][j], uu = acc[m][n + 2][j];
;             dst[f] = f2bf(siluf(g) * uu);
;           }
;         }
;       }
	v_add_u32_e32 v250, 0x30000, v248
	v_mul_f32_e32 v240, 0xbfb8aa3b, v80
	v_exp_f32_e32 v240, v240
	s_nop 0
	v_add_f32_e32 v240, 1.0, v240
	v_div_scale_f32 v241, s[8:9], v240, v240, v80
	v_rcp_f32_e32 v242, v241
	s_nop 0
	v_fma_f32 v243, -v241, v242, 1.0
	v_fmac_f32_e32 v242, v243, v242
	v_div_scale_f32 v243, vcc, v80, v240, v80
	v_mul_f32_e32 v245, v243, v242
	v_fma_f32 v246, -v241, v245, v243
	v_fmac_f32_e32 v245, v246, v242
	v_fma_f32 v241, -v241, v245, v243
	v_div_fmas_f32 v241, v241, v242, v245
	v_div_fixup_f32 v80, v241, v240, v80
	v_mul_f32_e32 v76, v76, v80
	v_bfe_u32 v80, v76, 16, 1
	v_add3_u32 v76, v76, v80, s33
	global_store_short_d16_hi v250, v76, s[6:7]
	v_mul_f32_e32 v240, 0xbfb8aa3b, v72
	v_exp_f32_e32 v240, v240
	s_nop 0
	v_add_f32_e32 v240, 1.0, v240
	v_div_scale_f32 v241, s[8:9], v240, v240, v72
	v_rcp_f32_e32 v242, v241
	s_nop 0
	v_fma_f32 v243, -v241, v242, 1.0
	v_fmac_f32_e32 v242, v243, v242
	v_div_scale_f32 v243, vcc, v72, v240, v72
	v_mul_f32_e32 v245, v243, v242
	v_fma_f32 v246, -v241, v245, v243
	v_fmac_f32_e32 v245, v246, v242
	v_fma_f32 v241, -v241, v245, v243
	v_div_fmas_f32 v241, v241, v242, v245
	v_div_fixup_f32 v72, v241, v240, v72
	v_mul_f32_e32 v68, v68, v72
	v_bfe_u32 v72, v68, 16, 1
	v_add3_u32 v68, v68, v72, s33
	global_store_short_d16_hi v250, v68, s[6:7] offset:32
	v_add_u32_e32 v250, 0x31000, v248
	v_mul_f32_e32 v240, 0xbfb8aa3b, v81
	v_exp_f32_e32 v240, v240
	s_nop 0
	v_add_f32_e32 v240, 1.0, v240
	v_div_scale_f32 v241, s[8:9], v240, v240, v81
	v_rcp_f32_e32 v242, v241
	s_nop 0
	v_fma_f32 v243, -v241, v242, 1.0
	v_fmac_f32_e32 v242, v243, v242
	v_div_scale_f32 v243, vcc, v81, v240, v81
	v_mul_f32_e32 v245, v243, v242
	v_fma_f32 v246, -v241, v245, v243
	v_fmac_f32_e32 v245, v246, v242
	v_fma_f32 v241, -v241, v245, v243
	v_div_fmas_f32 v241, v241, v242, v245
	v_div_fixup_f32 v81, v241, v240, v81
	v_mul_f32_e32 v77, v77, v81
	v_bfe_u32 v81, v77, 16, 1
	v_add3_u32 v77, v77, v81, s33
	global_store_short_d16_hi v250, v77, s[6:7]
	v_mul_f32_e32 v240, 0xbfb8aa3b, v73
	v_exp_f32_e32 v240, v240
	s_nop 0
	v_add_f32_e32 v240, 1.0, v240
	v_div_scale_f32 v241, s[8:9], v240, v240, v73
	v_rcp_f32_e32 v242, v241
	s_nop 0
	v_fma_f32 v243, -v241, v242, 1.0
	v_fmac_f32_e32 v242, v243, v242
	v_div_scale_f32 v243, vcc, v73, v240, v73
	v_mul_f32_e32 v245, v243, v242
	v_fma_f32 v246, -v241, v245, v243
	v_fmac_f32_e32 v245, v246, v242
	v_fma_f32 v241, -v241, v245, v243
	v_div_fmas_f32 v241, v241, v242, v245
	v_div_fixup_f32 v73, v241, v240, v73
	v_mul_f32_e32 v69, v69, v73
	v_bfe_u32 v73, v69, 16, 1
	v_add3_u32 v69, v69, v73, s33
	global_store_short_d16_hi v250, v69, s[6:7] offset:32
	v_add_u32_e32 v250, 0x32000, v248
	v_mul_f32_e32 v240, 0xbfb8aa3b, v82
	v_exp_f32_e32 v240, v240
	s_nop 0
	v_add_f32_e32 v240, 1.0, v240
	v_div_scale_f32 v241, s[8:9], v240, v240, v82
	v_rcp_f32_e32 v242, v241
	s_nop 0
	v_fma_f32 v243, -v241, v242, 1.0
	v_fmac_f32_e32 v242, v243, v242
	v_div_scale_f32 v243, vcc, v82, v240, v82
	v_mul_f32_e32 v245, v243, v242
	v_fma_f32 v246, -v241, v245, v243
	v_fmac_f32_e32 v245, v246, v242
	v_fma_f32 v241, -v241, v245, v243
	v_div_fmas_f32 v241, v241, v242, v245
	v_div_fixup_f32 v82, v241, v240, v82
	v_mul_f32_e32 v78, v78, v82
	v_bfe_u32 v82, v78, 16, 1
	v_add3_u32 v78, v78, v82, s33
	global_store_short_d16_hi v250, v78, s[6:7]
	v_mul_f32_e32 v240, 0xbfb8aa3b, v74
	v_exp_f32_e32 v240, v240
	s_nop 0
	v_add_f32_e32 v240, 1.0, v240
	v_div_scale_f32 v241, s[8:9], v240, v240, v74
	v_rcp_f32_e32 v242, v241
	s_nop 0
	v_fma_f32 v243, -v241, v242, 1.0
	v_fmac_f32_e32 v242, v243, v242
	v_div_scale_f32 v243, vcc, v74, v240, v74
	v_mul_f32_e32 v245, v243, v242
	v_fma_f32 v246, -v241, v245, v243
	v_fmac_f32_e32 v245, v246, v242
	v_fma_f32 v241, -v241, v245, v243
	v_div_fmas_f32 v241, v241, v242, v245
	v_div_fixup_f32 v74, v241, v240, v74
	v_mul_f32_e32 v70, v70, v74
	v_bfe_u32 v74, v70, 16, 1
	v_add3_u32 v70, v70, v74, s33
	global_store_short_d16_hi v250, v70, s[6:7] offset:32
	v_add_u32_e32 v250, 0x33000, v248
	v_mul_f32_e32 v240, 0xbfb8aa3b, v83
	v_exp_f32_e32 v240, v240
	s_nop 0
	v_add_f32_e32 v240, 1.0, v240
	v_div_scale_f32 v241, s[8:9], v240, v240, v83
	v_rcp_f32_e32 v242, v241
	s_nop 0
	v_fma_f32 v243, -v241, v242, 1.0
	v_fmac_f32_e32 v242, v243, v242
	v_div_scale_f32 v243, vcc, v83, v240, v83
	v_mul_f32_e32 v245, v243, v242
	v_fma_f32 v246, -v241, v245, v243
	v_fmac_f32_e32 v245, v246, v242
	v_fma_f32 v241, -v241, v245, v243
	v_div_fmas_f32 v241, v241, v242, v245
	v_div_fixup_f32 v83, v241, v240, v83
	v_mul_f32_e32 v79, v79, v83
	v_bfe_u32 v83, v79, 16, 1
	v_add3_u32 v79, v79, v83, s33
	global_store_short_d16_hi v250, v79, s[6:7]
	v_mul_f32_e32 v240, 0xbfb8aa3b, v75
	v_exp_f32_e32 v240, v240
	s_nop 0
	v_add_f32_e32 v240, 1.0, v240
	v_div_scale_f32 v241, s[8:9], v240, v240, v75
	v_rcp_f32_e32 v242, v241
	s_nop 0
	v_fma_f32 v243, -v241, v242, 1.0
	v_fmac_f32_e32 v242, v243, v242
	v_div_scale_f32 v243, vcc, v75, v240, v75
	v_mul_f32_e32 v245, v243, v242
	v_fma_f32 v246, -v241, v245, v243
	v_fmac_f32_e32 v245, v246, v242
	v_fma_f32 v241, -v241, v245, v243
	v_div_fmas_f32 v241, v241, v242, v245
	v_div_fixup_f32 v75, v241, v240, v75
	v_mul_f32_e32 v71, v71, v75
	v_bfe_u32 v75, v71, 16, 1
	v_add3_u32 v71, v71, v75, s33
	global_store_short_d16_hi v250, v71, s[6:7] offset:32
	v_add_u32_e32 v250, 0x40000, v248
	v_mul_f32_e32 v240, 0xbfb8aa3b, v64
	v_exp_f32_e32 v240, v240
	s_nop 0
	v_add_f32_e32 v240, 1.0, v240
	v_div_scale_f32 v241, s[8:9], v240, v240, v64
	v_rcp_f32_e32 v242, v241
	s_nop 0
	v_fma_f32 v243, -v241, v242, 1.0
	v_fmac_f32_e32 v242, v243, v242
	v_div_scale_f32 v243, vcc, v64, v240, v64
	v_mul_f32_e32 v245, v243, v242
; __device__ __forceinline__ float siluf(float x) { return x / (1.f + __expf(-x)); }
; __device__ __forceinline__ void moe_up_tile(const Params& p, char* smem, int l, int e, int nt, int b, int mt, bool isctx) {
;     ...
;   auto epi = [&](f32x4 (&acc)[8][4], int wr, int wc, int fr, int fq) {
; #pragma unroll
;     for (int m = 0; m < 8; ++m)
; #pragma unroll
;       for (int j = 0; j < 4; ++j) {
;         int slot = wr * 128 + m * 16 + fq * 4 + j;
;         if (slot < nvalid) {
;           u16* dst = isctx ? ACTC + ((size_t)(((slot >> 5) * 16 + e) * 32 + (slot & 31))) * 2048 : ACTL + (size_t)slot * 2048;
; #pragma unroll
;           for (int n = 0; n < 2; ++n) {
;             int f = nt * 64 + wc * 32 + n * 16 + fr;
;             float g = acc[m][n][j], uu = acc[m][n + 2][j];
;             dst[f] = f2bf(siluf(g) * uu);
;           }
;         }
;       }
	v_fma_f32 v246, -v241, v245, v243
	v_fmac_f32_e32 v245, v246, v242
	v_fma_f32 v241, -v241, v245, v243
	v_div_fmas_f32 v241, v241, v242, v245
	v_div_fixup_f32 v64, v241, v240, v64
	v_mul_f32_e32 v60, v60, v64
	v_bfe_u32 v64, v60, 16, 1
	v_add3_u32 v60, v60, v64, s33
	global_store_short_d16_hi v250, v60, s[6:7]
	v_mul_f32_e32 v240, 0xbfb8aa3b, v56
	v_exp_f32_e32 v240, v240
	s_nop 0
	v_add_f32_e32 v240, 1.0, v240
	v_div_scale_f32 v241, s[8:9], v240, v240, v56
	v_rcp_f32_e32 v242, v241
	s_nop 0
	v_fma_f32 v243, -v241, v242, 1.0
	v_fmac_f32_e32 v242, v243, v242
	v_div_scale_f32 v243, vcc, v56, v240, v56
	v_mul_f32_e32 v245, v243, v242
	v_fma_f32 v246, -v241, v245, v243
	v_fmac_f32_e32 v245, v246, v242
	v_fma_f32 v241, -v241, v245, v243
	v_div_fmas_f32 v241, v241, v242, v245
	v_div_fixup_f32 v56, v241, v240, v56
	v_mul_f32_e32 v52, v52, v56
	v_bfe_u32 v56, v52, 16, 1
	v_add3_u32 v52, v52, v56, s33
	global_store_short_d16_hi v250, v52, s[6:7] offset:32
	v_add_u32_e32 v250, 0x41000, v248
	v_mul_f32_e32 v240, 0xbfb8aa3b, v65
	v_exp_f32_e32 v240, v240
	s_nop 0
	v_add_f32_e32 v240, 1.0, v240
	v_div_scale_f32 v241, s[8:9], v240, v240, v65
	v_rcp_f32_e32 v242, v241
	s_nop 0
	v_fma_f32 v243, -v241, v242, 1.0
	v_fmac_f32_e32 v242, v243, v242
	v_div_scale_f32 v243, vcc, v65, v240, v65
	v_mul_f32_e32 v245, v243, v242
	v_fma_f32 v246, -v241, v245, v243
	v_fmac_f32_e32 v245, v246, v242
	v_fma_f32 v241, -v241, v245, v243
	v_div_fmas_f32 v241, v241, v242, v245
	v_div_fixup_f32 v65, v241, v240, v65
	v_mul_f32_e32 v61, v61, v65
	v_bfe_u32 v65, v61, 16, 1
	v_add3_u32 v61, v61, v65, s33
	global_store_short_d16_hi v250, v61, s[6:7]
	v_mul_f32_e32 v240, 0xbfb8aa3b, v57
	v_exp_f32_e32 v240, v240
	s_nop 0
	v_add_f32_e32 v240, 1.0, v240
	v_div_scale_f32 v241, s[8:9], v240, v240, v57
	v_rcp_f32_e32 v242, v241
	s_nop 0
	v_fma_f32 v243, -v241, v242, 1.0
	v_fmac_f32_e32 v242, v243, v242
	v_div_scale_f32 v243, vcc, v57, v240, v57
	v_mul_f32_e32 v245, v243, v242
	v_fma_f32 v246, -v241, v245, v243
	v_fmac_f32_e32 v245, v246, v242
	v_fma_f32 v241, -v241, v245, v243
	v_div_fmas_f32 v241, v241, v242, v245
	v_div_fixup_f32 v57, v241, v240, v57
	v_mul_f32_e32 v53, v53, v57
	v_bfe_u32 v57, v53, 16, 1
	v_add3_u32 v53, v53, v57, s33
	global_store_short_d16_hi v250, v53, s[6:7] offset:32
	v_add_u32_e32 v250, 0x42000, v248
	v_mul_f32_e32 v240, 0xbfb8aa3b, v66
	v_exp_f32_e32 v240, v240
	s_nop 0
	v_add_f32_e32 v240, 1.0, v240
	v_div_scale_f32 v241, s[8:9], v240, v240, v66
	v_rcp_f32_e32 v242, v241
	s_nop 0
	v_fma_f32 v243, -v241, v242, 1.0
	v_fmac_f32_e32 v242, v243, v242
	v_div_scale_f32 v243, vcc, v66, v240, v66
	v_mul_f32_e32 v245, v243, v242
	v_fma_f32 v246, -v241, v245, v243
	v_fmac_f32_e32 v245, v246, v242
	v_fma_f32 v241, -v241, v245, v243
	v_div_fmas_f32 v241, v241, v242, v245
	v_div_fixup_f32 v66, v241, v240, v66
	v_mul_f32_e32 v62, v62, v66
	v_bfe_u32 v66, v62, 16, 1
	v_add3_u32 v62, v62, v66, s33
	global_store_short_d16_hi v250, v62, s[6:7]
	v_mul_f32_e32 v240, 0xbfb8aa3b, v58
	v_exp_f32_e32 v240, v240
	s_nop 0
	v_add_f32_e32 v240, 1.0, v240
	v_div_scale_f32 v241, s[8:9], v240, v240, v58
	v_rcp_f32_e32 v242, v241
	s_nop 0
	v_fma_f32 v243, -v241, v242, 1.0
	v_fmac_f32_e32 v242, v243, v242
	v_div_scale_f32 v243, vcc, v58, v240, v58
	v_mul_f32_e32 v245, v243, v242
	v_fma_f32 v246, -v241, v245, v243
	v_fmac_f32_e32 v245, v246, v242
	v_fma_f32 v241, -v241, v245, v243
	v_div_fmas_f32 v241, v241, v242, v245
	v_div_fixup_f32 v58, v241, v240, v58
	v_mul_f32_e32 v54, v54, v58
	v_bfe_u32 v58, v54, 16, 1
	v_add3_u32 v54, v54, v58, s33
	global_store_short_d16_hi v250, v54, s[6:7] offset:32
	v_add_u32_e32 v250, 0x43000, v248
	v_mul_f32_e32 v240, 0xbfb8aa3b, v67
	v_exp_f32_e32 v240, v240
	s_nop 0
	v_add_f32_e32 v240, 1.0, v240
	v_div_scale_f32 v241, s[8:9], v240, v240, v67
	v_rcp_f32_e32 v242, v241
	s_nop 0
	v_fma_f32 v243, -v241, v242, 1.0
	v_fmac_f32_e32 v242, v243, v242
	v_div_scale_f32 v243, vcc, v67, v240, v67
	v_mul_f32_e32 v245, v243, v242
	v_fma_f32 v246, -v241, v245, v243
	v_fmac_f32_e32 v245, v246, v242
	v_fma_f32 v241, -v241, v245, v243
	v_div_fmas_f32 v241, v241, v242, v245
	v_div_fixup_f32 v67, v241, v240, v67
	v_mul_f32_e32 v63, v63, v67
	v_bfe_u32 v67, v63, 16, 1
	v_add3_u32 v63, v63, v67, s33
	global_store_short_d16_hi v250, v63, s[6:7]
	v_mul_f32_e32 v240, 0xbfb8aa3b, v59
	v_exp_f32_e32 v240, v240
	s_nop 0
	v_add_f32_e32 v240, 1.0, v240
	v_div_scale_f32 v241, s[8:9], v240, v240, v59
	v_rcp_f32_e32 v242, v241
	s_nop 0
	v_fma_f32 v243, -v241, v242, 1.0
	v_fmac_f32_e32 v242, v243, v242
	v_div_scale_f32 v243, vcc, v59, v240, v59
	v_mul_f32_e32 v245, v243, v242
	v_fma_f32 v246, -v241, v245, v243
	v_fmac_f32_e32 v245, v246, v242
	v_fma_f32 v241, -v241, v245, v243
	v_div_fmas_f32 v241, v241, v242, v245
	v_div_fixup_f32 v59, v241, v240, v59
	v_mul_f32_e32 v55, v55, v59
	v_bfe_u32 v59, v55, 16, 1
	v_add3_u32 v55, v55, v59, s33
	global_store_short_d16_hi v250, v55, s[6:7] offset:32
	v_add_u32_e32 v250, 0x50000, v248
	v_mul_f32_e32 v240, 0xbfb8aa3b, v48
	v_exp_f32_e32 v240, v240
	s_nop 0
	v_add_f32_e32 v240, 1.0, v240
	v_div_scale_f32 v241, s[8:9], v240, v240, v48
	v_rcp_f32_e32 v242, v241
	s_nop 0
	v_fma_f32 v243, -v241, v242, 1.0
	v_fmac_f32_e32 v242, v243, v242
	v_div_scale_f32 v243, vcc, v48, v240, v48
	v_mul_f32_e32 v245, v243, v242
	v_fma_f32 v246, -v241, v245, v243
	v_fmac_f32_e32 v245, v246, v242
	v_fma_f32 v241, -v241, v245, v243
	v_div_fmas_f32 v241, v241, v242, v245
	v_div_fixup_f32 v48, v241, v240, v48
	v_mul_f32_e32 v44, v44, v48
	v_bfe_u32 v48, v44, 16, 1
	v_add3_u32 v44, v44, v48, s33
	global_store_short_d16_hi v250, v44, s[6:7]
	v_mul_f32_e32 v240, 0xbfb8aa3b, v40
; __device__ __forceinline__ u16 f2bf(float f) {
;   unsigned u = __float_as_uint(f);
;   u += 0x7fffu + ((u >> 16) & 1u);
;   return (u16)(u >> 16);
; }
; __device__ __forceinline__ float bf2f(u16 h) { return __uint_as_float(((unsigned)h) << 16); }
; __device__ __forceinline__ unsigned pack2(float a, float b) { return (unsigned)f2bf(a) | ((unsigned)f2bf(b) << 16); }
; __device__ __forceinline__ float wave_sum(float v) {
; #pragma unroll
;   for (int o = 32; o > 0; o >>= 1) v += __shfl_xor(v, o);
;   return v;
; }
; __device__ __forceinline__ float siluf(float x) { return x / (1.f + __expf(-x)); }
; __device__ __forceinline__ void moe_up_tile(const Params& p, char* smem, int l, int e, int nt, int b, int mt, bool isctx) {
;     ...
; #pragma unroll
;     for (int m = 0; m < 8; ++m)
; #pragma unroll
;       for (int j = 0; j < 4; ++j) {
;         int slot = wr * 128 + m * 16 + fq * 4 + j;
;         if (slot < nvalid) {
;           u16* dst = isctx ? ACTC + ((size_t)(((slot >> 5) * 16 + e) * 32 + (slot & 31))) * 2048 : ACTL + (size_t)slot * 2048;
; #pragma unroll
;           for (int n = 0; n < 2; ++n) {
;             int f = nt * 64 + wc * 32 + n * 16 + fr;
;             float g = acc[m][n][j], uu = acc[m][n + 2][j];
;             dst[f] = f2bf(siluf(g) * uu);
;           }
	v_exp_f32_e32 v240, v240
	s_nop 0
	v_add_f32_e32 v240, 1.0, v240
	v_div_scale_f32 v241, s[8:9], v240, v240, v40
	v_rcp_f32_e32 v242, v241
	s_nop 0
	v_fma_f32 v243, -v241, v242, 1.0
	v_fmac_f32_e32 v242, v243, v242
	v_div_scale_f32 v243, vcc, v40, v240, v40
	v_mul_f32_e32 v245, v243, v242
	v_fma_f32 v246, -v241, v245, v243
	v_fmac_f32_e32 v245, v246, v242
	v_fma_f32 v241, -v241, v245, v243
	v_div_fmas_f32 v241, v241, v242, v245
	v_div_fixup_f32 v40, v241, v240, v40
	v_mul_f32_e32 v36, v36, v40
	v_bfe_u32 v40, v36, 16, 1
	v_add3_u32 v36, v36, v40, s33
	global_store_short_d16_hi v250, v36, s[6:7] offset:32
	v_add_u32_e32 v250, 0x51000, v248
	v_mul_f32_e32 v240, 0xbfb8aa3b, v49
	v_exp_f32_e32 v240, v240
	s_nop 0
	v_add_f32_e32 v240, 1.0, v240
	v_div_scale_f32 v241, s[8:9], v240, v240, v49
	v_rcp_f32_e32 v242, v241
	s_nop 0
	v_fma_f32 v243, -v241, v242, 1.0
	v_fmac_f32_e32 v242, v243, v242
	v_div_scale_f32 v243, vcc, v49, v240, v49
	v_mul_f32_e32 v245, v243, v242
	v_fma_f32 v246, -v241, v245, v243
	v_fmac_f32_e32 v245, v246, v242
	v_fma_f32 v241, -v241, v245, v243
	v_div_fmas_f32 v241, v241, v242, v245
	v_div_fixup_f32 v49, v241, v240, v49
	v_mul_f32_e32 v45, v45, v49
	v_bfe_u32 v49, v45, 16, 1
	v_add3_u32 v45, v45, v49, s33
	global_store_short_d16_hi v250, v45, s[6:7]
	v_mul_f32_e32 v240, 0xbfb8aa3b, v41
	v_exp_f32_e32 v240, v240
	s_nop 0
	v_add_f32_e32 v240, 1.0, v240
	v_div_scale_f32 v241, s[8:9], v240, v240, v41
	v_rcp_f32_e32 v242, v241
	s_nop 0
	v_fma_f32 v243, -v241, v242, 1.0
	v_fmac_f32_e32 v242, v243, v242
	v_div_scale_f32 v243, vcc, v41, v240, v41
	v_mul_f32_e32 v245, v243, v242
	v_fma_f32 v246, -v241, v245, v243
	v_fmac_f32_e32 v245, v246, v242
	v_fma_f32 v241, -v241, v245, v243
	v_div_fmas_f32 v241, v241, v242, v245
	v_div_fixup_f32 v41, v241, v240, v41
	v_mul_f32_e32 v37, v37, v41
	v_bfe_u32 v41, v37, 16, 1
	v_add3_u32 v37, v37, v41, s33
	global_store_short_d16_hi v250, v37, s[6:7] offset:32
	v_add_u32_e32 v250, 0x52000, v248
	v_mul_f32_e32 v240, 0xbfb8aa3b, v50
	v_exp_f32_e32 v240, v240
	s_nop 0
	v_add_f32_e32 v240, 1.0, v240
	v_div_scale_f32 v241, s[8:9], v240, v240, v50
	v_rcp_f32_e32 v242, v241
	s_nop 0
	v_fma_f32 v243, -v241, v242, 1.0
	v_fmac_f32_e32 v242, v243, v242
	v_div_scale_f32 v243, vcc, v50, v240, v50
	v_mul_f32_e32 v245, v243, v242
	v_fma_f32 v246, -v241, v245, v243
	v_fmac_f32_e32 v245, v246, v242
	v_fma_f32 v241, -v241, v245, v243
	v_div_fmas_f32 v241, v241, v242, v245
	v_div_fixup_f32 v50, v241, v240, v50
	v_mul_f32_e32 v46, v46, v50
	v_bfe_u32 v50, v46, 16, 1
	v_add3_u32 v46, v46, v50, s33
	global_store_short_d16_hi v250, v46, s[6:7]
	v_mul_f32_e32 v240, 0xbfb8aa3b, v42
	v_exp_f32_e32 v240, v240
	s_nop 0
	v_add_f32_e32 v240, 1.0, v240
	v_div_scale_f32 v241, s[8:9], v240, v240, v42
	v_rcp_f32_e32 v242, v241
	s_nop 0
	v_fma_f32 v243, -v241, v242, 1.0
	v_fmac_f32_e32 v242, v243, v242
	v_div_scale_f32 v243, vcc, v42, v240, v42
	v_mul_f32_e32 v245, v243, v242
	v_fma_f32 v246, -v241, v245, v243
	v_fmac_f32_e32 v245, v246, v242
	v_fma_f32 v241, -v241, v245, v243
	v_div_fmas_f32 v241, v241, v242, v245
	v_div_fixup_f32 v42, v241, v240, v42
	v_mul_f32_e32 v38, v38, v42
	v_bfe_u32 v42, v38, 16, 1
	v_add3_u32 v38, v38, v42, s33
	global_store_short_d16_hi v250, v38, s[6:7] offset:32
	v_add_u32_e32 v250, 0x53000, v248
	v_mul_f32_e32 v240, 0xbfb8aa3b, v51
	v_exp_f32_e32 v240, v240
	s_nop 0
	v_add_f32_e32 v240, 1.0, v240
	v_div_scale_f32 v241, s[8:9], v240, v240, v51
	v_rcp_f32_e32 v242, v241
	s_nop 0
	v_fma_f32 v243, -v241, v242, 1.0
	v_fmac_f32_e32 v242, v243, v242
	v_div_scale_f32 v243, vcc, v51, v240, v51
	v_mul_f32_e32 v245, v243, v242
	v_fma_f32 v246, -v241, v245, v243
	v_fmac_f32_e32 v245, v246, v242
	v_fma_f32 v241, -v241, v245, v243
	v_div_fmas_f32 v241, v241, v242, v245
	v_div_fixup_f32 v51, v241, v240, v51
	v_mul_f32_e32 v47, v47, v51
	v_bfe_u32 v51, v47, 16, 1
	v_add3_u32 v47, v47, v51, s33
	global_store_short_d16_hi v250, v47, s[6:7]
	v_mul_f32_e32 v240, 0xbfb8aa3b, v43
	v_exp_f32_e32 v240, v240
	s_nop 0
	v_add_f32_e32 v240, 1.0, v240
	v_div_scale_f32 v241, s[8:9], v240, v240, v43
	v_rcp_f32_e32 v242, v241
	s_nop 0
	v_fma_f32 v243, -v241, v242, 1.0
	v_fmac_f32_e32 v242, v243, v242
	v_div_scale_f32 v243, vcc, v43, v240, v43
	v_mul_f32_e32 v245, v243, v242
	v_fma_f32 v246, -v241, v245, v243
	v_fmac_f32_e32 v245, v246, v242
	v_fma_f32 v241, -v241, v245, v243
	v_div_fmas_f32 v241, v241, v242, v245
	v_div_fixup_f32 v43, v241, v240, v43
	v_mul_f32_e32 v39, v39, v43
	v_bfe_u32 v43, v39, 16, 1
	v_add3_u32 v39, v39, v43, s33
	global_store_short_d16_hi v250, v39, s[6:7] offset:32
	v_add_u32_e32 v250, 0x60000, v248
	v_mul_f32_e32 v240, 0xbfb8aa3b, v32
	v_exp_f32_e32 v240, v240
	s_nop 0
	v_add_f32_e32 v240, 1.0, v240
	v_div_scale_f32 v241, s[8:9], v240, v240, v32
	v_rcp_f32_e32 v242, v241
	s_nop 0
	v_fma_f32 v243, -v241, v242, 1.0
	v_fmac_f32_e32 v242, v243, v242
	v_div_scale_f32 v243, vcc, v32, v240, v32
	v_mul_f32_e32 v245, v243, v242
	v_fma_f32 v246, -v241, v245, v243
	v_fmac_f32_e32 v245, v246, v242
	v_fma_f32 v241, -v241, v245, v243
	v_div_fmas_f32 v241, v241, v242, v245
	v_div_fixup_f32 v32, v241, v240, v32
	v_mul_f32_e32 v28, v28, v32
	v_bfe_u32 v32, v28, 16, 1
	v_add3_u32 v28, v28, v32, s33
	global_store_short_d16_hi v250, v28, s[6:7]
	v_mul_f32_e32 v240, 0xbfb8aa3b, v24
	v_exp_f32_e32 v240, v240
	s_nop 0
	v_add_f32_e32 v240, 1.0, v240
	v_div_scale_f32 v241, s[8:9], v240, v240, v24
	v_rcp_f32_e32 v242, v241
	s_nop 0
	v_fma_f32 v243, -v241, v242, 1.0
	v_fmac_f32_e32 v242, v243, v242
	v_div_scale_f32 v243, vcc, v24, v240, v24
	v_mul_f32_e32 v245, v243, v242
	v_fma_f32 v246, -v241, v245, v243
	v_fmac_f32_e32 v245, v246, v242
; __device__ __forceinline__ u16 f2bf(float f) {
;   unsigned u = __float_as_uint(f);
;   u += 0x7fffu + ((u >> 16) & 1u);
;   return (u16)(u >> 16);
; }
; __device__ __forceinline__ float bf2f(u16 h) { return __uint_as_float(((unsigned)h) << 16); }
; __device__ __forceinline__ unsigned pack2(float a, float b) { return (unsigned)f2bf(a) | ((unsigned)f2bf(b) << 16); }
; __device__ __forceinline__ float wave_sum(float v) {
; #pragma unroll
;   for (int o = 32; o > 0; o >>= 1) v += __shfl_xor(v, o);
;   return v;
; }
; __device__ __forceinline__ float siluf(float x) { return x / (1.f + __expf(-x)); }
; __device__ __forceinline__ void moe_up_tile(const Params& p, char* smem, int l, int e, int nt, int b, int mt, bool isctx) {
;     ...
; #pragma unroll
;     for (int m = 0; m < 8; ++m)
; #pragma unroll
;       for (int j = 0; j < 4; ++j) {
;         int slot = wr * 128 + m * 16 + fq * 4 + j;
;         if (slot < nvalid) {
;           u16* dst = isctx ? ACTC + ((size_t)(((slot >> 5) * 16 + e) * 32 + (slot & 31))) * 2048 : ACTL + (size_t)slot * 2048;
; #pragma unroll
;           for (int n = 0; n < 2; ++n) {
;             int f = nt * 64 + wc * 32 + n * 16 + fr;
;             float g = acc[m][n][j], uu = acc[m][n + 2][j];
;             dst[f] = f2bf(siluf(g) * uu);
;           }
	v_fma_f32 v241, -v241, v245, v243
	v_div_fmas_f32 v241, v241, v242, v245
	v_div_fixup_f32 v24, v241, v240, v24
	v_mul_f32_e32 v20, v20, v24
	v_bfe_u32 v24, v20, 16, 1
	v_add3_u32 v20, v20, v24, s33
	global_store_short_d16_hi v250, v20, s[6:7] offset:32
	v_add_u32_e32 v250, 0x61000, v248
	v_mul_f32_e32 v240, 0xbfb8aa3b, v33
	v_exp_f32_e32 v240, v240
	s_nop 0
	v_add_f32_e32 v240, 1.0, v240
	v_div_scale_f32 v241, s[8:9], v240, v240, v33
	v_rcp_f32_e32 v242, v241
	s_nop 0
	v_fma_f32 v243, -v241, v242, 1.0
	v_fmac_f32_e32 v242, v243, v242
	v_div_scale_f32 v243, vcc, v33, v240, v33
	v_mul_f32_e32 v245, v243, v242
	v_fma_f32 v246, -v241, v245, v243
	v_fmac_f32_e32 v245, v246, v242
	v_fma_f32 v241, -v241, v245, v243
	v_div_fmas_f32 v241, v241, v242, v245
	v_div_fixup_f32 v33, v241, v240, v33
	v_mul_f32_e32 v29, v29, v33
	v_bfe_u32 v33, v29, 16, 1
	v_add3_u32 v29, v29, v33, s33
	global_store_short_d16_hi v250, v29, s[6:7]
	v_mul_f32_e32 v240, 0xbfb8aa3b, v25
	v_exp_f32_e32 v240, v240
	s_nop 0
	v_add_f32_e32 v240, 1.0, v240
	v_div_scale_f32 v241, s[8:9], v240, v240, v25
	v_rcp_f32_e32 v242, v241
	s_nop 0
	v_fma_f32 v243, -v241, v242, 1.0
	v_fmac_f32_e32 v242, v243, v242
	v_div_scale_f32 v243, vcc, v25, v240, v25
	v_mul_f32_e32 v245, v243, v242
	v_fma_f32 v246, -v241, v245, v243
	v_fmac_f32_e32 v245, v246, v242
	v_fma_f32 v241, -v241, v245, v243
	v_div_fmas_f32 v241, v241, v242, v245
	v_div_fixup_f32 v25, v241, v240, v25
	v_mul_f32_e32 v21, v21, v25
	v_bfe_u32 v25, v21, 16, 1
	v_add3_u32 v21, v21, v25, s33
	global_store_short_d16_hi v250, v21, s[6:7] offset:32
	v_add_u32_e32 v250, 0x62000, v248
	v_mul_f32_e32 v240, 0xbfb8aa3b, v34
	v_exp_f32_e32 v240, v240
	s_nop 0
	v_add_f32_e32 v240, 1.0, v240
	v_div_scale_f32 v241, s[8:9], v240, v240, v34
	v_rcp_f32_e32 v242, v241
	s_nop 0
	v_fma_f32 v243, -v241, v242, 1.0
	v_fmac_f32_e32 v242, v243, v242
	v_div_scale_f32 v243, vcc, v34, v240, v34
	v_mul_f32_e32 v245, v243, v242
	v_fma_f32 v246, -v241, v245, v243
	v_fmac_f32_e32 v245, v246, v242
	v_fma_f32 v241, -v241, v245, v243
	v_div_fmas_f32 v241, v241, v242, v245
	v_div_fixup_f32 v34, v241, v240, v34
	v_mul_f32_e32 v30, v30, v34
	v_bfe_u32 v34, v30, 16, 1
	v_add3_u32 v30, v30, v34, s33
	global_store_short_d16_hi v250, v30, s[6:7]
	v_mul_f32_e32 v240, 0xbfb8aa3b, v26
	v_exp_f32_e32 v240, v240
	s_nop 0
	v_add_f32_e32 v240, 1.0, v240
	v_div_scale_f32 v241, s[8:9], v240, v240, v26
	v_rcp_f32_e32 v242, v241
	s_nop 0
	v_fma_f32 v243, -v241, v242, 1.0
	v_fmac_f32_e32 v242, v243, v242
	v_div_scale_f32 v243, vcc, v26, v240, v26
	v_mul_f32_e32 v245, v243, v242
	v_fma_f32 v246, -v241, v245, v243
	v_fmac_f32_e32 v245, v246, v242
	v_fma_f32 v241, -v241, v245, v243
	v_div_fmas_f32 v241, v241, v242, v245
	v_div_fixup_f32 v26, v241, v240, v26
	v_mul_f32_e32 v22, v22, v26
	v_bfe_u32 v26, v22, 16, 1
	v_add3_u32 v22, v22, v26, s33
	global_store_short_d16_hi v250, v22, s[6:7] offset:32
	v_add_u32_e32 v250, 0x63000, v248
	v_mul_f32_e32 v240, 0xbfb8aa3b, v35
	v_exp_f32_e32 v240, v240
	s_nop 0
	v_add_f32_e32 v240, 1.0, v240
	v_div_scale_f32 v241, s[8:9], v240, v240, v35
	v_rcp_f32_e32 v242, v241
	s_nop 0
	v_fma_f32 v243, -v241, v242, 1.0
	v_fmac_f32_e32 v242, v243, v242
	v_div_scale_f32 v243, vcc, v35, v240, v35
	v_mul_f32_e32 v245, v243, v242
	v_fma_f32 v246, -v241, v245, v243
	v_fmac_f32_e32 v245, v246, v242
	v_fma_f32 v241, -v241, v245, v243
	v_div_fmas_f32 v241, v241, v242, v245
	v_div_fixup_f32 v35, v241, v240, v35
	v_mul_f32_e32 v31, v31, v35
	v_bfe_u32 v35, v31, 16, 1
	v_add3_u32 v31, v31, v35, s33
	global_store_short_d16_hi v250, v31, s[6:7]
	v_mul_f32_e32 v240, 0xbfb8aa3b, v27
	v_exp_f32_e32 v240, v240
	s_nop 0
	v_add_f32_e32 v240, 1.0, v240
	v_div_scale_f32 v241, s[8:9], v240, v240, v27
	v_rcp_f32_e32 v242, v241
	s_nop 0
	v_fma_f32 v243, -v241, v242, 1.0
	v_fmac_f32_e32 v242, v243, v242
	v_div_scale_f32 v243, vcc, v27, v240, v27
	v_mul_f32_e32 v245, v243, v242
	v_fma_f32 v246, -v241, v245, v243
	v_fmac_f32_e32 v245, v246, v242
	v_fma_f32 v241, -v241, v245, v243
	v_div_fmas_f32 v241, v241, v242, v245
	v_div_fixup_f32 v27, v241, v240, v27
	v_mul_f32_e32 v23, v23, v27
	v_bfe_u32 v27, v23, 16, 1
	v_add3_u32 v23, v23, v27, s33
	global_store_short_d16_hi v250, v23, s[6:7] offset:32
	v_add_u32_e32 v250, 0x70000, v248
	v_mul_f32_e32 v240, 0xbfb8aa3b, v16
	v_exp_f32_e32 v240, v240
	s_nop 0
	v_add_f32_e32 v240, 1.0, v240
	v_div_scale_f32 v241, s[8:9], v240, v240, v16
	v_rcp_f32_e32 v242, v241
	s_nop 0
	v_fma_f32 v243, -v241, v242, 1.0
	v_fmac_f32_e32 v242, v243, v242
	v_div_scale_f32 v243, vcc, v16, v240, v16
	v_mul_f32_e32 v245, v243, v242
	v_fma_f32 v246, -v241, v245, v243
	v_fmac_f32_e32 v245, v246, v242
	v_fma_f32 v241, -v241, v245, v243
	v_div_fmas_f32 v241, v241, v242, v245
	v_div_fixup_f32 v16, v241, v240, v16
	v_mul_f32_e32 v12, v12, v16
	v_bfe_u32 v16, v12, 16, 1
	v_add3_u32 v12, v12, v16, s33
	global_store_short_d16_hi v250, v12, s[6:7]
	v_mul_f32_e32 v240, 0xbfb8aa3b, v8
	v_exp_f32_e32 v240, v240
	s_nop 0
	v_add_f32_e32 v240, 1.0, v240
	v_div_scale_f32 v241, s[8:9], v240, v240, v8
	v_rcp_f32_e32 v242, v241
	s_nop 0
	v_fma_f32 v243, -v241, v242, 1.0
	v_fmac_f32_e32 v242, v243, v242
	v_div_scale_f32 v243, vcc, v8, v240, v8
	v_mul_f32_e32 v245, v243, v242
	v_fma_f32 v246, -v241, v245, v243
	v_fmac_f32_e32 v245, v246, v242
	v_fma_f32 v241, -v241, v245, v243
	v_div_fmas_f32 v241, v241, v242, v245
	v_div_fixup_f32 v8, v241, v240, v8
	v_mul_f32_e32 v4, v4, v8
	v_bfe_u32 v8, v4, 16, 1
	v_add3_u32 v4, v4, v8, s33
	global_store_short_d16_hi v250, v4, s[6:7] offset:32
	v_add_u32_e32 v250, 0x71000, v248
	v_mul_f32_e32 v240, 0xbfb8aa3b, v17
	v_exp_f32_e32 v240, v240
	s_nop 0
; __device__ __forceinline__ u16 f2bf(float f) {
;   unsigned u = __float_as_uint(f);
;   u += 0x7fffu + ((u >> 16) & 1u);
;   return (u16)(u >> 16);
; }
; __device__ __forceinline__ float bf2f(u16 h) { return __uint_as_float(((unsigned)h) << 16); }
; __device__ __forceinline__ unsigned pack2(float a, float b) { return (unsigned)f2bf(a) | ((unsigned)f2bf(b) << 16); }
; __device__ __forceinline__ float wave_sum(float v) {
; #pragma unroll
;   for (int o = 32; o > 0; o >>= 1) v += __shfl_xor(v, o);
;   return v;
; }
; __device__ __forceinline__ float siluf(float x) { return x / (1.f + __expf(-x)); }
; __device__ __forceinline__ void moe_up_tile(const Params& p, char* smem, int l, int e, int nt, int b, int mt, bool isctx) {
;     ...
; #pragma unroll
;     for (int m = 0; m < 8; ++m)
; #pragma unroll
;       for (int j = 0; j < 4; ++j) {
;         int slot = wr * 128 + m * 16 + fq * 4 + j;
;         if (slot < nvalid) {
;           u16* dst = isctx ? ACTC + ((size_t)(((slot >> 5) * 16 + e) * 32 + (slot & 31))) * 2048 : ACTL + (size_t)slot * 2048;
; #pragma unroll
;           for (int n = 0; n < 2; ++n) {
;             int f = nt * 64 + wc * 32 + n * 16 + fr;
;             float g = acc[m][n][j], uu = acc[m][n + 2][j];
;             dst[f] = f2bf(siluf(g) * uu);
;           }
	v_add_f32_e32 v240, 1.0, v240
	v_div_scale_f32 v241, s[8:9], v240, v240, v17
	v_rcp_f32_e32 v242, v241
	s_nop 0
	v_fma_f32 v243, -v241, v242, 1.0
	v_fmac_f32_e32 v242, v243, v242
	v_div_scale_f32 v243, vcc, v17, v240, v17
	v_mul_f32_e32 v245, v243, v242
	v_fma_f32 v246, -v241, v245, v243
	v_fmac_f32_e32 v245, v246, v242
	v_fma_f32 v241, -v241, v245, v243
	v_div_fmas_f32 v241, v241, v242, v245
	v_div_fixup_f32 v17, v241, v240, v17
	v_mul_f32_e32 v13, v13, v17
	v_bfe_u32 v17, v13, 16, 1
	v_add3_u32 v13, v13, v17, s33
	global_store_short_d16_hi v250, v13, s[6:7]
	v_mul_f32_e32 v240, 0xbfb8aa3b, v9
	v_exp_f32_e32 v240, v240
	s_nop 0
	v_add_f32_e32 v240, 1.0, v240
	v_div_scale_f32 v241, s[8:9], v240, v240, v9
	v_rcp_f32_e32 v242, v241
	s_nop 0
	v_fma_f32 v243, -v241, v242, 1.0
	v_fmac_f32_e32 v242, v243, v242
	v_div_scale_f32 v243, vcc, v9, v240, v9
	v_mul_f32_e32 v245, v243, v242
	v_fma_f32 v246, -v241, v245, v243
	v_fmac_f32_e32 v245, v246, v242
	v_fma_f32 v241, -v241, v245, v243
	v_div_fmas_f32 v241, v241, v242, v245
	v_div_fixup_f32 v9, v241, v240, v9
	v_mul_f32_e32 v5, v5, v9
	v_bfe_u32 v9, v5, 16, 1
	v_add3_u32 v5, v5, v9, s33
	global_store_short_d16_hi v250, v5, s[6:7] offset:32
	v_add_u32_e32 v250, 0x72000, v248
	v_mul_f32_e32 v240, 0xbfb8aa3b, v18
	v_exp_f32_e32 v240, v240
	s_nop 0
	v_add_f32_e32 v240, 1.0, v240
	v_div_scale_f32 v241, s[8:9], v240, v240, v18
	v_rcp_f32_e32 v242, v241
	s_nop 0
	v_fma_f32 v243, -v241, v242, 1.0
	v_fmac_f32_e32 v242, v243, v242
	v_div_scale_f32 v243, vcc, v18, v240, v18
	v_mul_f32_e32 v245, v243, v242
	v_fma_f32 v246, -v241, v245, v243
	v_fmac_f32_e32 v245, v246, v242
	v_fma_f32 v241, -v241, v245, v243
	v_div_fmas_f32 v241, v241, v242, v245
	v_div_fixup_f32 v18, v241, v240, v18
	v_mul_f32_e32 v14, v14, v18
	v_bfe_u32 v18, v14, 16, 1
	v_add3_u32 v14, v14, v18, s33
	global_store_short_d16_hi v250, v14, s[6:7]
	v_mul_f32_e32 v240, 0xbfb8aa3b, v10
	v_exp_f32_e32 v240, v240
	s_nop 0
	v_add_f32_e32 v240, 1.0, v240
	v_div_scale_f32 v241, s[8:9], v240, v240, v10
	v_rcp_f32_e32 v242, v241
	s_nop 0
	v_fma_f32 v243, -v241, v242, 1.0
	v_fmac_f32_e32 v242, v243, v242
	v_div_scale_f32 v243, vcc, v10, v240, v10
	v_mul_f32_e32 v245, v243, v242
	v_fma_f32 v246, -v241, v245, v243
	v_fmac_f32_e32 v245, v246, v242
	v_fma_f32 v241, -v241, v245, v243
	v_div_fmas_f32 v241, v241, v242, v245
	v_div_fixup_f32 v10, v241, v240, v10
	v_mul_f32_e32 v6, v6, v10
	v_bfe_u32 v10, v6, 16, 1
	v_add3_u32 v6, v6, v10, s33
	global_store_short_d16_hi v250, v6, s[6:7] offset:32
	v_add_u32_e32 v250, 0x73000, v248
	v_mul_f32_e32 v240, 0xbfb8aa3b, v19
	v_exp_f32_e32 v240, v240
	s_nop 0
	v_add_f32_e32 v240, 1.0, v240
	v_div_scale_f32 v241, s[8:9], v240, v240, v19
	v_rcp_f32_e32 v242, v241
	s_nop 0
	v_fma_f32 v243, -v241, v242, 1.0
	v_fmac_f32_e32 v242, v243, v242
	v_div_scale_f32 v243, vcc, v19, v240, v19
	v_mul_f32_e32 v245, v243, v242
	v_fma_f32 v246, -v241, v245, v243
	v_fmac_f32_e32 v245, v246, v242
	v_fma_f32 v241, -v241, v245, v243
	v_div_fmas_f32 v241, v241, v242, v245
	v_div_fixup_f32 v19, v241, v240, v19
	v_mul_f32_e32 v15, v15, v19
	v_bfe_u32 v19, v15, 16, 1
	v_add3_u32 v15, v15, v19, s33
	global_store_short_d16_hi v250, v15, s[6:7]
	v_mul_f32_e32 v240, 0xbfb8aa3b, v11
	v_exp_f32_e32 v240, v240
	s_nop 0
	v_add_f32_e32 v240, 1.0, v240
	v_div_scale_f32 v241, s[8:9], v240, v240, v11
	v_rcp_f32_e32 v242, v241
	s_nop 0
	v_fma_f32 v243, -v241, v242, 1.0
	v_fmac_f32_e32 v242, v243, v242
	v_div_scale_f32 v243, vcc, v11, v240, v11
	v_mul_f32_e32 v245, v243, v242
	v_fma_f32 v246, -v241, v245, v243
	v_fmac_f32_e32 v245, v246, v242
	v_fma_f32 v241, -v241, v245, v243
	v_div_fmas_f32 v241, v241, v242, v245
	v_div_fixup_f32 v11, v241, v240, v11
	v_mul_f32_e32 v7, v7, v11
	v_bfe_u32 v11, v7, 16, 1
	v_add3_u32 v7, v7, v11, s33
	global_store_short_d16_hi v250, v7, s[6:7] offset:32
	s_mov_b64 s[0:1], exec
	s_branch .LBB0_1639
.Lp6_epi_slow:
	s_and_saveexec_b64 s[0:1], vcc
	s_cbranch_execz .LBB0_1675
	v_add_u32_e32 v133, s13, v3
	v_lshl_or_b32 v133, v133, 5, v2
	v_cndmask_b32_e64 v134, v132, v133, s[38:39]
	v_mul_f32_e32 v133, 0xbfb8aa3b, v128
	v_exp_f32_e32 v133, v133
	s_and_b64 s[8:9], s[38:39], exec
	v_ashrrev_i32_e32 v135, 31, v134
	s_cselect_b32 s9, s5, s7
	s_cselect_b32 s8, s4, s6
	v_lshlrev_b64 v[134:135], 12, v[134:135]
	v_add_f32_e32 v133, 1.0, v133
	v_lshl_add_u64 v[134:135], s[8:9], 0, v[134:135]
	v_div_scale_f32 v136, s[8:9], v133, v133, v128
	v_rcp_f32_e32 v137, v136
	s_nop 0
	v_fma_f32 v138, -v136, v137, 1.0
	v_fmac_f32_e32 v137, v138, v137
	v_div_scale_f32 v138, vcc, v128, v133, v128
	v_mul_f32_e32 v139, v138, v137
	v_fma_f32 v140, -v136, v139, v138
	v_fmac_f32_e32 v139, v140, v137
	v_fma_f32 v136, -v136, v139, v138
	v_div_fmas_f32 v136, v136, v137, v139
	v_div_fixup_f32 v128, v136, v133, v128
	v_mul_f32_e32 v124, v124, v128
	v_bfe_u32 v128, v124, 16, 1
	v_add3_u32 v124, v124, v128, s33
	v_lshlrev_b32_e32 v128, 1, v0
	v_lshl_or_b32 v136, s10, 7, v128
	v_mov_b32_e32 v137, v1
	v_lshl_add_u64 v[134:135], v[134:135], 0, v[136:137]
	global_store_short_d16_hi v[134:135], v124, off
	v_mul_f32_e32 v124, 0xbfb8aa3b, v120
	v_exp_f32_e32 v124, v124
	s_nop 0
	v_add_f32_e32 v124, 1.0, v124
	v_div_scale_f32 v128, s[8:9], v124, v124, v120
	v_rcp_f32_e32 v133, v128
	s_nop 0
	v_fma_f32 v136, -v128, v133, 1.0
	v_fmac_f32_e32 v133, v136, v133
	v_div_scale_f32 v136, vcc, v120, v124, v120
	v_mul_f32_e32 v137, v136, v133
	v_fma_f32 v138, -v128, v137, v136
	v_fmac_f32_e32 v137, v138, v133
	v_fma_f32 v128, -v128, v137, v136
	v_div_fmas_f32 v128, v128, v133, v137
	v_div_fixup_f32 v120, v128, v124, v120
	v_mul_f32_e32 v116, v116, v120
	v_bfe_u32 v120, v116, 16, 1
	v_add3_u32 v116, v116, v120, s33
	global_store_short_d16_hi v[134:135], v116, off offset:32
